# adds: G5 rowss loads hoisted, merge loop loads issued together + next-trip touch, mLSTM gate scans via DPP, G4 rowss atomics deferred to epilogue end
# speedup vs baseline: 1.0263x; 1.0041x over previous
.LBB0_364:
	s_and_b64 s[20:21], s[72:73], s[24:25]
	s_andn2_b64 vcc, exec, s[20:21]
	s_cbranch_vccnz .LBB0_366
	s_mov_b32 s20, 0x3fb8aa3b
	v_mov_b32_e32 v8, v125
	s_nop 1
	v_add_f32_dpp v8, v8, v8 row_shr:1 row_mask:0xf bank_mask:0xf
	s_nop 1
	v_add_f32_dpp v8, v8, v8 row_shr:2 row_mask:0xf bank_mask:0xf
	s_nop 1
	v_add_f32_dpp v8, v8, v8 row_shr:4 row_mask:0xf bank_mask:0xf
	s_nop 1
	v_add_f32_dpp v8, v8, v8 row_shr:8 row_mask:0xf bank_mask:0xf
	s_nop 1
	v_add_f32_dpp v8, v8, v8 row_bcast:15 row_mask:0xa bank_mask:0xf
	s_nop 1
	v_add_f32_dpp v8, v8, v8 row_bcast:31 row_mask:0xc bank_mask:0xf
	v_sub_f32_e32 v3, v139, v8
	v_mov_b32_e32 v0, v3
	s_nop 1
	v_max_f32_dpp v0, v0, v0 row_shr:1 row_mask:0xf bank_mask:0xf
	s_nop 1
	v_max_f32_dpp v0, v0, v0 row_shr:2 row_mask:0xf bank_mask:0xf
	s_nop 1
	v_max_f32_dpp v0, v0, v0 row_shr:4 row_mask:0xf bank_mask:0xf
	s_nop 1
	v_max_f32_dpp v0, v0, v0 row_shr:8 row_mask:0xf bank_mask:0xf
	s_nop 1
	v_max_f32_dpp v0, v0, v0 row_bcast:15 row_mask:0xa bank_mask:0xf
	s_nop 1
	v_max_f32_dpp v0, v0, v0 row_bcast:31 row_mask:0xc bank_mask:0xf
	v_max_f32_e32 v0, v0, v0
	v_max_f32_e32 v2, v154, v154
	v_max_f32_e32 v2, v2, v0
	v_lshl_or_b32 v0, v194, 2, v196
	ds_bpermute_b32 v4, v0, v8
	ds_bpermute_b32 v0, v0, v2
	v_pk_mul_f32 v[126:127], v[2:3], s[20:21] op_sel_hi:[1,0]
	v_sub_f32_e32 v5, v154, v2
	v_add_f32_e32 v2, v8, v2
	v_mul_f32_e32 v2, 0xbfb8aa3b, v2
	v_exp_f32_e32 v158, v2
	s_waitcnt lgkmcnt(0)
	v_sub_f32_e32 v2, v3, v0
	v_mul_f32_e32 v2, 0x3fb8aa3b, v2
	v_exp_f32_e32 v159, v2
	v_sub_f32_e32 v2, v154, v0
	v_mul_f32_e32 v5, 0x3fb8aa3b, v5
	v_mul_f32_e32 v2, 0x3fb8aa3b, v2
	v_exp_f32_e32 v157, v5
	v_exp_f32_e32 v160, v2
	v_add_f32_e32 v154, v4, v0

; DI float lo_f(unsigned u) { return __uint_as_float(u << 16); }
; DI float hi_f(unsigned u) { return __uint_as_float(u & 0xffff0000u); }
; DI unsigned pk2(float lo, float hi) { return pg8::cvt_pk_bf16(lo, hi); }
; __global__ void __launch_bounds__(512, 2) fwd_mega(Args a) {
;     ...
;         for (int i = bx * 512 + tid; i < TH * 64; i += G * 512) {
;             const int tok = i >> 6, rem = i & 63, hs = rem >> 4, ch = rem & 15;
;             const float l0 = LSE[tok * 12 + hs], l1 = LSE[tok * 12 + 4 + hs], l2 = LSE[tok * 12 + 8 + hs];
;             const float mx = fmaxf(l0, fmaxf(l1, l2)); float w0 = __expf(l0 - mx), w1 = __expf(l1 - mx), w2 = __expf(l2 - mx); const float inv = 1.0f / (w0 + w1 + w2); w0 *= inv; w1 *= inv; w2 *= inv;
;             const size_t off = (size_t)tok * 512 + hs * 128 + ch * 8;
;             const v4u o0 = *(const v4u*)(OG + off), o1 = *(const v4u*)(OG + (size_t)TH * 512 + off), o2 = *(const v4u*)(OG + (size_t)2 * TH * 512 + off);
;             v4u r;
;             r.x = pk2(w0 * lo_f(o0.x) + w1 * lo_f(o1.x) + w2 * lo_f(o2.x), w0 * hi_f(o0.x) + w1 * hi_f(o1.x) + w2 * hi_f(o2.x));
;             r.y = pk2(w0 * lo_f(o0.y) + w1 * lo_f(o1.y) + w2 * lo_f(o2.y), w0 * hi_f(o0.y) + w1 * hi_f(o1.y) + w2 * hi_f(o2.y));
;             r.z = pk2(w0 * lo_f(o0.z) + w1 * lo_f(o1.z) + w2 * lo_f(o2.z), w0 * hi_f(o0.z) + w1 * hi_f(o1.z) + w2 * hi_f(o2.z));
;             r.w = pk2(w0 * lo_f(o0.w) + w1 * lo_f(o1.w) + w2 * lo_f(o2.w), w0 * hi_f(o0.w) + w1 * hi_f(o1.w) + w2 * hi_f(o2.w));
;             *(v4u*)(ATT + off) = r;
;         } }
.LBB0_493:
	v_ashrrev_i32_e32 v4, 6, v0
	v_bfe_u32 v3, v0, 4, 2
	v_mul_lo_u32 v5, v4, 12
	v_or_b32_e32 v6, v5, v3
	v_ashrrev_i32_e32 v7, 31, v6
	v_lshl_add_u64 v[8:9], v[6:7], 2, s[90:91]
	global_load_dword v5, v[8:9], off
	v_add_u32_e32 v8, 4, v6
	v_add_u32_e32 v6, 8, v6
	v_ashrrev_i32_e32 v9, 31, v8
	v_ashrrev_i32_e32 v7, 31, v6
	v_lshl_add_u64 v[8:9], v[8:9], 2, s[90:91]
	v_lshl_add_u64 v[6:7], v[6:7], 2, s[90:91]
	global_load_dword v8, v[8:9], off
	v_lshlrev_b32_e32 v3, 7, v3
	global_load_dword v6, v[6:7], off
	v_add_u32_e32 v0, s50, v0
	v_mov_b32_e32 v28, v4
	v_ashrrev_i32_e32 v29, 31, v4
	v_lshlrev_b64 v[28:29], 9, v[28:29]
	v_and_b32_e32 v30, 0x78, v2
	v_or3_b32 v28, v28, v3, v30
	v_lshlrev_b64 v[20:21], 1, v[28:29]
	v_lshl_add_u64 v[32:33], s[88:89], 0, v[20:21]
	v_lshl_add_u64 v[34:35], s[30:31], 0, v[20:21]
	v_lshl_add_u64 v[36:37], s[48:49], 0, v[20:21]
	global_load_dwordx4 v[40:43], v[32:33], off
	global_load_dwordx4 v[44:47], v[34:35], off
	global_load_dwordx4 v[48:51], v[36:37], off
	v_ashrrev_i32_e32 v52, 6, v0
	v_bfe_u32 v54, v0, 4, 2
	v_ashrrev_i32_e32 v53, 31, v52
	v_add_u32_e32 v55, s6, v2
	v_lshlrev_b64 v[52:53], 9, v[52:53]
	v_lshlrev_b32_e32 v54, 7, v54
	v_and_b32_e32 v55, 0x78, v55
	v_or3_b32 v52, v52, v54, v55
	v_lshlrev_b64 v[52:53], 1, v[52:53]
	v_lshl_add_u64 v[54:55], s[88:89], 0, v[52:53]
	v_lshl_add_u64 v[56:57], s[30:31], 0, v[52:53]
	v_lshl_add_u64 v[58:59], s[48:49], 0, v[52:53]
	global_load_dword v60, v[54:55], off
	global_load_dword v60, v[56:57], off
	global_load_dword v60, v[58:59], off
	s_waitcnt vmcnt(6)
	v_max3_f32 v7, v5, v8, v6
	v_sub_f32_e32 v5, v5, v7
	v_mul_f32_e32 v5, 0x3fb8aa3b, v5
	v_exp_f32_e32 v17, v5
	v_sub_f32_e32 v5, v8, v7
	v_mul_f32_e32 v5, 0x3fb8aa3b, v5
	v_sub_f32_e32 v6, v6, v7
	v_exp_f32_e32 v5, v5
	v_mul_f32_e32 v6, 0x3fb8aa3b, v6
	v_exp_f32_e32 v16, v6
	v_add_f32_e32 v6, v17, v5
	v_add_f32_e32 v6, v16, v6
	v_div_scale_f32 v7, s[4:5], v6, v6, 1.0
	v_rcp_f32_e32 v8, v7
	s_mov_b32 s4, 0x1fffff
	v_fma_f32 v9, -v7, v8, 1.0
	v_fmac_f32_e32 v8, v9, v8
	v_div_scale_f32 v9, vcc, 1.0, v6, 1.0
	v_mul_f32_e32 v10, v9, v8
	v_fma_f32 v11, -v7, v10, v9
	v_fmac_f32_e32 v10, v11, v8
	v_fma_f32 v7, -v7, v10, v9
	v_div_fmas_f32 v7, v7, v8, v10
	v_div_fixup_f32 v18, v7, v6, 1.0
	v_mul_f32_e32 v19, v5, v18
	s_waitcnt vmcnt(3)
	v_mov_b32_e32 v4, v40
	v_mov_b32_e32 v5, v41
	v_mov_b32_e32 v6, v42
	v_mov_b32_e32 v7, v43
	v_mov_b32_e32 v8, v44
	v_mov_b32_e32 v9, v45
	v_mov_b32_e32 v10, v46
	v_mov_b32_e32 v11, v47
	v_mov_b32_e32 v12, v48
	v_mov_b32_e32 v13, v49
	v_mov_b32_e32 v14, v50
	v_mov_b32_e32 v15, v51
	v_cmp_lt_i32_e32 vcc, s4, v0
	v_add_u32_e32 v2, s6, v2
	s_or_b64 s[2:3], vcc, s[2:3]
	v_lshlrev_b32_e32 v3, 16, v8
	v_and_b32_e32 v22, 0xffff0000, v8
	v_lshlrev_b32_e32 v23, 16, v9
	v_and_b32_e32 v24, 0xffff0000, v9
	v_pk_mul_f32 v[8:9], v[16:17], v[18:19] op_sel_hi:[1,0]
	v_lshlrev_b32_e32 v17, 16, v4
	v_lshlrev_b32_e32 v16, 16, v12
	v_pk_mul_f32 v[16:17], v[8:9], v[16:17]
	v_lshlrev_b32_e32 v25, 16, v10
	v_fma_f32 v3, v19, v3, v17
	v_add_f32_e32 v3, v16, v3
	v_and_b32_e32 v17, 0xffff0000, v4
	v_and_b32_e32 v16, 0xffff0000, v12
	v_pk_mul_f32 v[16:17], v[8:9], v[16:17]
	v_and_b32_e32 v10, 0xffff0000, v10
	v_fma_f32 v4, v19, v22, v17
	v_add_f32_e32 v4, v16, v4
	v_lshlrev_b32_e32 v17, 16, v5
	v_lshlrev_b32_e32 v16, 16, v13
	v_pk_mul_f32 v[16:17], v[8:9], v[16:17]
	v_cvt_pk_bf16_f32 v4, v3, v4
	v_lshlrev_b32_e32 v26, 16, v11
	v_fma_f32 v3, v19, v23, v17
	v_add_f32_e32 v3, v16, v3
	v_and_b32_e32 v17, 0xffff0000, v5
	v_and_b32_e32 v16, 0xffff0000, v13
	v_pk_mul_f32 v[12:13], v[8:9], v[16:17]
	s_nop 0
	v_fma_f32 v5, v19, v24, v13
	v_add_f32_e32 v5, v12, v5
	v_lshlrev_b32_e32 v13, 16, v6
	v_lshlrev_b32_e32 v12, 16, v14
	v_pk_mul_f32 v[12:13], v[8:9], v[12:13]
	v_cvt_pk_bf16_f32 v5, v3, v5
	s_nop 0
	v_fma_f32 v3, v19, v25, v13
	v_add_f32_e32 v3, v12, v3
	v_and_b32_e32 v13, 0xffff0000, v6
	v_and_b32_e32 v12, 0xffff0000, v14
	v_pk_mul_f32 v[12:13], v[8:9], v[12:13]
	s_nop 0
	v_fma_f32 v6, v19, v10, v13
	v_add_f32_e32 v6, v12, v6
	v_lshlrev_b32_e32 v13, 16, v7
	v_lshlrev_b32_e32 v12, 16, v15
	v_pk_mul_f32 v[12:13], v[8:9], v[12:13]
	v_cvt_pk_bf16_f32 v6, v3, v6
	v_and_b32_e32 v10, 0xffff0000, v15
	v_fma_f32 v3, v19, v26, v13
	v_add_f32_e32 v3, v12, v3
	v_and_b32_e32 v12, 0xffff0000, v11
	v_and_b32_e32 v11, 0xffff0000, v7
	v_pk_mul_f32 v[8:9], v[8:9], v[10:11]
	s_nop 0
	v_fma_f32 v7, v19, v12, v9
	v_add_f32_e32 v7, v8, v7
	v_lshl_add_u64 v[8:9], s[92:93], 0, v[20:21]
	v_cvt_pk_bf16_f32 v7, v3, v7
	global_store_dwordx4 v[8:9], v[4:7], off
	s_andn2_b64 exec, exec, s[2:3]
	s_cbranch_execnz .LBB0_493

; DI unsigned pk2(float lo, float hi) { return pg8::cvt_pk_bf16(lo, hi); }
;     DI void operator()(const f32x4 (&acc)[2][2][4][2], const Unit& u, int wr, int wc, int fr, int fq) const {
;         const int row0 = u.pm * 256 + wr * 64 + fr, col0 = u.pn * 256 + wc * 32 + 8 * fq;
;         const int b = (grow0 + u.pm * 256) >> 11;
;         f32x4 g[2][2], gm[2][2];
; #pragma unroll
;         for (int bj = 0; bj < 2; ++bj) { const int c = col0 + bj * 128; const float* gp = ada + (size_t)b * 6144 + 2048 + c; const float* sp = ada + (size_t)b * 6144 + 4096 + c;
;             g[bj][0] = *(const f32x4*)gp; g[bj][1] = *(const f32x4*)(gp + 4);
;             gm[bj][0] = *(const f32x4*)(g2 + c) * (*(const f32x4*)sp + 1.0f); gm[bj][1] = *(const f32x4*)(g2 + c + 4) * (*(const f32x4*)(sp + 4) + 1.0f); }
; #pragma unroll
;         for (int ai = 0; ai < 2; ++ai)
; #pragma unroll
;             for (int m = 0; m < 4; ++m) { const size_t r = (size_t)(row0 + ai * 128 + m * 16); float ss = 0.f;
; #pragma unroll
;                 for (int bj = 0; bj < 2; ++bj) { const size_t off = r * 1024 + col0 + bj * 128;
;                     f32x4 v0 = *(const f32x4*)(base + off), v1 = *(const f32x4*)(base + off + 4);
;                     v0 += g[bj][0] * acc[ai][bj][m][0]; v1 += g[bj][1] * acc[ai][bj][m][1];
;                     *(f32x4*)(out + off) = v0; *(f32x4*)(out + off + 4) = v1;
;                     ss += (v0[0] * v0[0] + v0[1] * v0[1]) + (v0[2] * v0[2] + v0[3] * v0[3]) + (v1[0] * v1[0] + v1[1] * v1[1]) + (v1[2] * v1[2] + v1[3] * v1[3]);
;                     const f32x4 u0 = v0 * gm[bj][0], u1 = v1 * gm[bj][1];
;                     v4u w; w.x = pk2(u0[0], u0[1]); w.y = pk2(u0[2], u0[3]); w.z = pk2(u1[0], u1[1]); w.w = pk2(u1[2], u1[3]);
;                     *(v4u*)(U2 + off) = w; }
;                 ss += __shfl_xor(ss, 16); ss += __shfl_xor(ss, 32);
;                 if (fq == 0) atomicAdd(rowss + r, ss); }
.LBB0_654:
	s_lshl_b32 s19, s42, 8
	v_readlane_b32 s26, v254, 56
	s_add_i32 s21, s19, s26
	s_ashr_i32 s21, s21, 11
	s_mul_hi_i32 s26, s21, 0x6000
	s_mulk_i32 s21, 0x6000
	v_readlane_b32 s28, v251, 8
	v_readlane_b32 s29, v251, 9
	s_add_u32 s21, s28, s21
	s_addc_u32 s29, s29, s26
	v_add_u32_e32 v184, s19, v186
	v_lshl_or_b32 v182, s41, 8, v199
	v_readlane_b32 s27, v254, 57
	s_add_u32 s26, s21, 0x2000
	v_ashrrev_i32_e32 v185, 31, v184
	s_addc_u32 s27, s29, 0
	v_ashrrev_i32_e32 v183, 31, v182
	v_lshlrev_b64 v[84:85], 10, v[184:185]
	v_lshl_add_u64 v[156:157], v[84:85], 0, v[182:183]
	s_add_u32 s28, s21, 0x4000
	v_lshlrev_b64 v[90:91], 2, v[182:183]
	v_lshlrev_b64 v[92:93], 2, v[156:157]
	s_addc_u32 s29, s29, 0
	v_lshl_add_u64 v[82:83], s[26:27], 0, v[90:91]
	v_lshl_add_u64 v[162:163], s[14:15], 0, v[92:93]
	v_lshl_add_u64 v[94:95], s[28:29], 0, v[90:91]
	global_load_dwordx4 v[158:161], v[162:163], off
	global_load_dwordx4 v[86:89], v[82:83], off
	s_nop 0
	global_load_dwordx4 v[82:85], v[82:83], off offset:16
	s_nop 0
	global_load_dwordx4 v[178:181], v[162:163], off offset:16
	global_load_dwordx4 v[202:205], v[94:95], off
	global_load_dwordx4 v[206:209], v[94:95], off offset:16
	v_lshl_add_u64 v[90:91], s[62:63], 0, v[90:91]
	global_load_dwordx4 v[210:213], v[90:91], off
	global_load_dwordx4 v[214:217], v[90:91], off offset:16
	v_or_b32_e32 v94, 0x80, v182
	v_ashrrev_i32_e32 v95, 31, v94
	v_lshlrev_b64 v[164:165], 2, v[94:95]
	v_lshl_add_u64 v[94:95], s[26:27], 0, v[164:165]
	v_lshl_add_u64 v[164:165], s[28:29], 0, v[164:165]
	global_load_dwordx4 v[218:221], v[90:91], off offset:528
	global_load_dwordx4 v[222:225], v[90:91], off offset:512
	v_lshl_add_u64 v[234:235], s[8:9], 0, v[92:93]
	global_load_dwordx4 v[90:93], v[94:95], off offset:16
	s_nop 0
	global_load_dwordx4 v[94:97], v[94:95], off
	s_nop 0
	global_load_dwordx4 v[226:229], v[164:165], off offset:16
	global_load_dwordx4 v[230:233], v[164:165], off
	v_lshl_add_u64 v[190:191], v[156:157], 1, s[10:11]
	v_readlane_b32 s30, v251, 10
	v_readlane_b32 s31, v251, 11
	s_waitcnt vmcnt(0)
	v_pk_fma_f32 v[158:159], v[142:143], v[86:87], v[158:159]
	v_pk_fma_f32 v[160:161], v[144:145], v[88:89], v[160:161]
	v_pk_add_f32 v[142:143], v[202:203], 1.0 op_sel_hi:[1,0]
	v_pk_add_f32 v[202:203], v[206:207], 1.0 op_sel_hi:[1,0]
	v_pk_fma_f32 v[178:179], v[138:139], v[82:83], v[178:179]
	v_pk_add_f32 v[138:139], v[204:205], 1.0 op_sel_hi:[1,0]
	v_pk_add_f32 v[164:165], v[208:209], 1.0 op_sel_hi:[1,0]
	v_pk_mul_f32 v[144:145], v[210:211], v[142:143]
	v_pk_mul_f32 v[142:143], v[214:215], v[202:203]
	v_pk_fma_f32 v[180:181], v[140:141], v[84:85], v[180:181]
	v_pk_mul_f32 v[140:141], v[212:213], v[138:139]
	v_pk_mul_f32 v[138:139], v[216:217], v[164:165]
	v_pk_mul_f32 v[202:203], v[144:145], v[158:159]
	v_pk_mul_f32 v[204:205], v[142:143], v[178:179]
	global_store_dwordx4 v[234:235], v[158:161], off
	global_store_dwordx4 v[234:235], v[178:181], off offset:16
	v_pk_mul_f32 v[164:165], v[140:141], v[160:161]
	v_pk_mul_f32 v[206:207], v[138:139], v[180:181]
	v_cvt_pk_bf16_f32 v202, v202, v203
	v_cvt_pk_bf16_f32 v203, v164, v165
	v_cvt_pk_bf16_f32 v204, v204, v205
	v_xor_b32_e32 v164, 32, v194
	v_cvt_pk_bf16_f32 v205, v206, v207
	global_store_dwordx4 v[190:191], v[202:205], off
	global_load_dwordx4 v[202:205], v[162:163], off offset:512
	s_nop 0
	global_load_dwordx4 v[206:209], v[162:163], off offset:528
	v_and_b32_e32 v163, 64, v194
	v_xor_b32_e32 v162, 16, v194
	v_add_u32_e32 v163, 64, v163
	v_cmp_lt_i32_e32 vcc, v162, v163
	v_mul_f32_e32 v215, v159, v159
	v_mul_f32_e32 v216, v161, v161
	v_cndmask_b32_e32 v162, v194, v162, vcc
	v_cmp_lt_i32_e32 vcc, v164, v163
	v_mul_f32_e32 v217, v179, v179
	v_lshlrev_b32_e32 v201, 2, v162
	v_cndmask_b32_e32 v214, v194, v164, vcc
	v_pk_add_f32 v[164:165], v[230:231], 1.0 op_sel_hi:[1,0]
	v_mul_f32_e32 v236, v181, v181
	v_pk_add_f32 v[162:163], v[232:233], 1.0 op_sel_hi:[1,0]
	v_fmac_f32_e32 v215, v158, v158
	v_fmac_f32_e32 v216, v160, v160
	v_fmac_f32_e32 v217, v178, v178
	v_pk_mul_f32 v[178:179], v[222:223], v[164:165]
	v_fmac_f32_e32 v236, v180, v180
	v_pk_mul_f32 v[180:181], v[224:225], v[162:163]
	v_add_f32_e32 v162, v215, v216
	v_pk_add_f32 v[210:211], v[228:229], 1.0 op_sel_hi:[1,0]
	v_add_f32_e32 v162, v162, v217
	v_pk_mul_f32 v[158:159], v[220:221], v[210:211]
	v_add_f32_e32 v210, v236, v162
	v_pk_add_f32 v[212:213], v[226:227], 1.0 op_sel_hi:[1,0]
	s_waitcnt vmcnt(1)
	v_pk_fma_f32 v[136:137], v[136:137], v[96:97], v[204:205]
	v_pk_fma_f32 v[134:135], v[134:135], v[94:95], v[202:203]
	s_waitcnt vmcnt(0)
	v_pk_fma_f32 v[130:131], v[130:131], v[90:91], v[206:207]
	v_mul_f32_e32 v202, v135, v135
	v_mul_f32_e32 v203, v137, v137
	v_pk_fma_f32 v[132:133], v[132:133], v[92:93], v[208:209]
	v_mul_f32_e32 v204, v131, v131
	v_fmac_f32_e32 v202, v134, v134
	v_fmac_f32_e32 v203, v136, v136
	global_store_dwordx4 v[234:235], v[134:137], off offset:512
	global_store_dwordx4 v[234:235], v[130:133], off offset:528
	v_mul_f32_e32 v205, v133, v133
	v_pk_mul_f32 v[164:165], v[178:179], v[134:135]
	v_fmac_f32_e32 v204, v130, v130
	v_add_f32_e32 v134, v202, v203
	v_fmac_f32_e32 v205, v132, v132
	v_add_f32_e32 v134, v134, v204
	v_add_f32_e32 v134, v205, v134
	v_add_f32_e32 v134, v210, v134
	ds_bpermute_b32 v135, v201, v134
	v_pk_mul_f32 v[162:163], v[180:181], v[136:137]
	v_pk_mul_f32 v[136:137], v[158:159], v[132:133]
	v_lshlrev_b32_e32 v132, 2, v214
	v_pk_mul_f32 v[160:161], v[218:219], v[212:213]
	s_waitcnt lgkmcnt(0)
	v_add_f32_e32 v133, v134, v135
	ds_bpermute_b32 v134, v132, v133
	v_pk_mul_f32 v[130:131], v[160:161], v[130:131]
	v_cvt_pk_bf16_f32 v202, v164, v165
	v_cvt_pk_bf16_f32 v203, v162, v163
	s_nop 0
	v_cvt_pk_bf16_f32 v204, v130, v131
	v_lshl_add_u64 v[130:131], v[184:185], 2, s[12:13]
	v_cvt_pk_bf16_f32 v205, v136, v137
	global_store_dwordx4 v[190:191], v[202:205], off offset:256
	s_and_saveexec_b64 s[26:27], s[4:5]
	s_cbranch_execz .LBB0_656
	s_waitcnt lgkmcnt(0)
	v_add_f32_e32 v133, v133, v134
	v_mov_b32_e32 v248, v133
; DI unsigned pk2(float lo, float hi) { return pg8::cvt_pk_bf16(lo, hi); }
;     DI void operator()(const f32x4 (&acc)[2][2][4][2], const Unit& u, int wr, int wc, int fr, int fq) const {
;     ...
;             for (int m = 0; m < 4; ++m) { const size_t r = (size_t)(row0 + ai * 128 + m * 16); float ss = 0.f;
; #pragma unroll
;                 for (int bj = 0; bj < 2; ++bj) { const size_t off = r * 1024 + col0 + bj * 128;
;                     f32x4 v0 = *(const f32x4*)(base + off), v1 = *(const f32x4*)(base + off + 4);
;                     v0 += g[bj][0] * acc[ai][bj][m][0]; v1 += g[bj][1] * acc[ai][bj][m][1];
;                     *(f32x4*)(out + off) = v0; *(f32x4*)(out + off + 4) = v1;
;                     ss += (v0[0] * v0[0] + v0[1] * v0[1]) + (v0[2] * v0[2] + v0[3] * v0[3]) + (v1[0] * v1[0] + v1[1] * v1[1]) + (v1[2] * v1[2] + v1[3] * v1[3]);
;                     const f32x4 u0 = v0 * gm[bj][0], u1 = v1 * gm[bj][1];
;                     v4u w; w.x = pk2(u0[0], u0[1]); w.y = pk2(u0[2], u0[3]); w.z = pk2(u1[0], u1[1]); w.w = pk2(u1[2], u1[3]);
;                     *(v4u*)(U2 + off) = w; }
;                 ss += __shfl_xor(ss, 16); ss += __shfl_xor(ss, 32);
;                 if (fq == 0) atomicAdd(rowss + r, ss); }
.LBB0_656:
	s_or_b64 exec, exec, s[26:27]
	s_waitcnt lgkmcnt(0)
	v_or_b32_e32 v134, 16, v184
	v_ashrrev_i32_e32 v135, 31, v134
	v_lshlrev_b64 v[134:135], 10, v[134:135]
	v_lshl_add_u64 v[162:163], v[134:135], 0, v[182:183]
	v_lshlrev_b64 v[164:165], 2, v[162:163]
	v_lshl_add_u64 v[190:191], s[14:15], 0, v[164:165]
	global_load_dwordx4 v[134:137], v[190:191], off
	global_load_dwordx4 v[202:205], v[190:191], off offset:16
	v_lshl_add_u64 v[162:163], v[162:163], 1, s[10:11]
	v_lshl_add_u64 v[164:165], s[8:9], 0, v[164:165]
	s_waitcnt vmcnt(1)
	v_pk_fma_f32 v[128:129], v[128:129], v[88:89], v[136:137]
	v_pk_fma_f32 v[126:127], v[126:127], v[86:87], v[134:135]
	s_waitcnt vmcnt(0)
	v_pk_fma_f32 v[124:125], v[124:125], v[84:85], v[204:205]
	v_pk_fma_f32 v[122:123], v[122:123], v[82:83], v[202:203]
	v_pk_mul_f32 v[136:137], v[140:141], v[128:129]
	v_pk_mul_f32 v[134:135], v[144:145], v[126:127]
	global_store_dwordx4 v[164:165], v[126:129], off
	global_store_dwordx4 v[164:165], v[122:125], off offset:16
	v_pk_mul_f32 v[202:203], v[138:139], v[124:125]
	v_pk_mul_f32 v[204:205], v[142:143], v[122:123]
	v_cvt_pk_bf16_f32 v134, v134, v135
	v_cvt_pk_bf16_f32 v135, v136, v137
	v_mul_f32_e32 v127, v127, v127
	v_cvt_pk_bf16_f32 v136, v204, v205
	v_cvt_pk_bf16_f32 v137, v202, v203
	global_store_dwordx4 v[162:163], v[134:137], off
	global_load_dwordx4 v[134:137], v[190:191], off offset:512
	s_nop 0
	global_load_dwordx4 v[202:205], v[190:191], off offset:528
	v_mul_f32_e32 v129, v129, v129
	v_mul_f32_e32 v123, v123, v123
	v_fmac_f32_e32 v127, v126, v126
	v_fmac_f32_e32 v129, v128, v128
	v_mul_f32_e32 v125, v125, v125
	v_fmac_f32_e32 v123, v122, v122
	v_add_f32_e32 v122, v127, v129
	v_fmac_f32_e32 v125, v124, v124
	v_add_f32_e32 v122, v122, v123
	v_add_f32_e32 v122, v125, v122
	s_waitcnt vmcnt(1)
	v_pk_fma_f32 v[120:121], v[120:121], v[96:97], v[136:137]
	v_pk_fma_f32 v[118:119], v[118:119], v[94:95], v[134:135]
	s_waitcnt vmcnt(0)
	v_pk_fma_f32 v[114:115], v[114:115], v[90:91], v[202:203]
	v_mul_f32_e32 v123, v119, v119
	v_mul_f32_e32 v124, v121, v121
	v_pk_fma_f32 v[116:117], v[116:117], v[92:93], v[204:205]
	v_mul_f32_e32 v125, v115, v115
	v_fmac_f32_e32 v123, v118, v118
	v_fmac_f32_e32 v124, v120, v120
	v_mul_f32_e32 v126, v117, v117
	v_fmac_f32_e32 v125, v114, v114
	v_add_f32_e32 v123, v123, v124
	v_fmac_f32_e32 v126, v116, v116
	v_add_f32_e32 v123, v123, v125
	v_add_f32_e32 v123, v126, v123
	v_add_f32_e32 v126, v122, v123
	ds_bpermute_b32 v127, v201, v126
	global_store_dwordx4 v[164:165], v[118:121], off offset:512
	global_store_dwordx4 v[164:165], v[114:117], off offset:528
	v_pk_mul_f32 v[124:125], v[160:161], v[114:115]
	v_pk_mul_f32 v[118:119], v[178:179], v[118:119]
	v_pk_mul_f32 v[120:121], v[180:181], v[120:121]
	s_waitcnt lgkmcnt(0)
	v_add_f32_e32 v114, v126, v127
	ds_bpermute_b32 v115, v132, v114
	v_pk_mul_f32 v[122:123], v[158:159], v[116:117]
	v_cvt_pk_bf16_f32 v116, v118, v119
	v_cvt_pk_bf16_f32 v117, v120, v121
	v_cvt_pk_bf16_f32 v118, v124, v125
	s_nop 0
	v_cvt_pk_bf16_f32 v119, v122, v123
	global_store_dwordx4 v[162:163], v[116:119], off offset:256
	s_and_saveexec_b64 s[26:27], s[4:5]
	v_readlane_b32 s30, v254, 34
	v_readlane_b32 s31, v254, 35
	s_cbranch_execz .LBB0_658
	s_waitcnt lgkmcnt(0)
	v_add_f32_e32 v114, v114, v115
	v_mov_b32_e32 v244, v114
.LBB0_658:
	s_or_b64 exec, exec, s[26:27]
	v_or_b32_e32 v114, 32, v184
	s_waitcnt lgkmcnt(0)
	v_ashrrev_i32_e32 v115, 31, v114
	v_lshlrev_b64 v[114:115], 10, v[114:115]
	v_lshl_add_u64 v[122:123], v[114:115], 0, v[182:183]
	v_lshlrev_b64 v[124:125], 2, v[122:123]
	v_lshl_add_u64 v[126:127], s[14:15], 0, v[124:125]
	global_load_dwordx4 v[114:117], v[126:127], off
	global_load_dwordx4 v[118:121], v[126:127], off offset:16
	v_lshl_add_u64 v[122:123], v[122:123], 1, s[10:11]
	v_lshl_add_u64 v[124:125], s[8:9], 0, v[124:125]
	s_waitcnt vmcnt(1)
	v_pk_fma_f32 v[112:113], v[112:113], v[88:89], v[116:117]
	v_pk_fma_f32 v[110:111], v[110:111], v[86:87], v[114:115]
	s_waitcnt vmcnt(0)
	v_pk_fma_f32 v[108:109], v[108:109], v[84:85], v[120:121]
	v_pk_fma_f32 v[106:107], v[106:107], v[82:83], v[118:119]
	v_pk_mul_f32 v[116:117], v[140:141], v[112:113]
	v_pk_mul_f32 v[114:115], v[144:145], v[110:111]
	global_store_dwordx4 v[124:125], v[110:113], off
	global_store_dwordx4 v[124:125], v[106:109], off offset:16
	v_pk_mul_f32 v[118:119], v[138:139], v[108:109]
	v_pk_mul_f32 v[120:121], v[142:143], v[106:107]
	v_cvt_pk_bf16_f32 v114, v114, v115
	v_cvt_pk_bf16_f32 v115, v116, v117
	v_mul_f32_e32 v111, v111, v111
	v_cvt_pk_bf16_f32 v116, v120, v121
	v_cvt_pk_bf16_f32 v117, v118, v119
	global_store_dwordx4 v[122:123], v[114:117], off
	global_load_dwordx4 v[114:117], v[126:127], off offset:512
	s_nop 0
	global_load_dwordx4 v[118:121], v[126:127], off offset:528
	v_mul_f32_e32 v113, v113, v113
	v_mul_f32_e32 v107, v107, v107
	v_fmac_f32_e32 v111, v110, v110
	v_fmac_f32_e32 v113, v112, v112
	v_mul_f32_e32 v109, v109, v109
	v_fmac_f32_e32 v107, v106, v106
	v_add_f32_e32 v106, v111, v113
	v_fmac_f32_e32 v109, v108, v108
	v_add_f32_e32 v106, v106, v107
	v_add_f32_e32 v106, v109, v106
	s_waitcnt vmcnt(1)
	v_pk_fma_f32 v[104:105], v[104:105], v[96:97], v[116:117]
	v_pk_fma_f32 v[102:103], v[102:103], v[94:95], v[114:115]
	s_waitcnt vmcnt(0)
	v_pk_fma_f32 v[98:99], v[98:99], v[90:91], v[118:119]
	v_mul_f32_e32 v107, v103, v103
	v_mul_f32_e32 v108, v105, v105
	v_pk_fma_f32 v[100:101], v[100:101], v[92:93], v[120:121]
	v_mul_f32_e32 v109, v99, v99
	v_fmac_f32_e32 v107, v102, v102
	v_fmac_f32_e32 v108, v104, v104
	v_mul_f32_e32 v110, v101, v101
	v_fmac_f32_e32 v109, v98, v98
	v_add_f32_e32 v107, v107, v108
	v_fmac_f32_e32 v110, v100, v100
	v_add_f32_e32 v107, v107, v109
	v_add_f32_e32 v107, v110, v107
	v_add_f32_e32 v110, v106, v107
	ds_bpermute_b32 v111, v201, v110
	global_store_dwordx4 v[124:125], v[102:105], off offset:512
	global_store_dwordx4 v[124:125], v[98:101], off offset:528
	v_pk_mul_f32 v[108:109], v[160:161], v[98:99]
	v_pk_mul_f32 v[102:103], v[178:179], v[102:103]
	v_pk_mul_f32 v[104:105], v[180:181], v[104:105]
	s_waitcnt lgkmcnt(0)
	v_add_f32_e32 v98, v110, v111
	ds_bpermute_b32 v99, v132, v98
	v_pk_mul_f32 v[106:107], v[158:159], v[100:101]
	v_cvt_pk_bf16_f32 v100, v102, v103
	v_cvt_pk_bf16_f32 v101, v104, v105
	v_cvt_pk_bf16_f32 v102, v108, v109
	s_nop 0
	v_cvt_pk_bf16_f32 v103, v106, v107
	global_store_dwordx4 v[122:123], v[100:103], off offset:256
	s_and_saveexec_b64 s[26:27], s[4:5]
	v_readlane_b32 s48, v254, 36
	v_readlane_b32 s49, v254, 37
	v_readlane_b32 s50, v254, 38
	s_cbranch_execz .LBB0_660
	s_waitcnt lgkmcnt(0)
	v_add_f32_e32 v98, v98, v99
	v_mov_b32_e32 v245, v98
; DI unsigned pk2(float lo, float hi) { return pg8::cvt_pk_bf16(lo, hi); }
;     DI void operator()(const f32x4 (&acc)[2][2][4][2], const Unit& u, int wr, int wc, int fr, int fq) const {
;     ...
;             for (int m = 0; m < 4; ++m) { const size_t r = (size_t)(row0 + ai * 128 + m * 16); float ss = 0.f;
; #pragma unroll
;                 for (int bj = 0; bj < 2; ++bj) { const size_t off = r * 1024 + col0 + bj * 128;
;                     f32x4 v0 = *(const f32x4*)(base + off), v1 = *(const f32x4*)(base + off + 4);
;                     v0 += g[bj][0] * acc[ai][bj][m][0]; v1 += g[bj][1] * acc[ai][bj][m][1];
;                     *(f32x4*)(out + off) = v0; *(f32x4*)(out + off + 4) = v1;
;                     ss += (v0[0] * v0[0] + v0[1] * v0[1]) + (v0[2] * v0[2] + v0[3] * v0[3]) + (v1[0] * v1[0] + v1[1] * v1[1]) + (v1[2] * v1[2] + v1[3] * v1[3]);
;                     const f32x4 u0 = v0 * gm[bj][0], u1 = v1 * gm[bj][1];
;                     v4u w; w.x = pk2(u0[0], u0[1]); w.y = pk2(u0[2], u0[3]); w.z = pk2(u1[0], u1[1]); w.w = pk2(u1[2], u1[3]);
;                     *(v4u*)(U2 + off) = w; }
;                 ss += __shfl_xor(ss, 16); ss += __shfl_xor(ss, 32);
;                 if (fq == 0) atomicAdd(rowss + r, ss); }
.LBB0_660:
	s_or_b64 exec, exec, s[26:27]
	v_or_b32_e32 v98, 48, v184
	s_waitcnt lgkmcnt(0)
	v_ashrrev_i32_e32 v99, 31, v98
	v_lshlrev_b64 v[98:99], 10, v[98:99]
	v_lshl_add_u64 v[106:107], v[98:99], 0, v[182:183]
	v_lshlrev_b64 v[108:109], 2, v[106:107]
	v_lshl_add_u64 v[110:111], s[14:15], 0, v[108:109]
	global_load_dwordx4 v[98:101], v[110:111], off
	global_load_dwordx4 v[102:105], v[110:111], off offset:16
	v_lshl_add_u64 v[106:107], v[106:107], 1, s[10:11]
	v_lshl_add_u64 v[108:109], s[8:9], 0, v[108:109]
	s_waitcnt vmcnt(1)
	v_pk_fma_f32 v[80:81], v[80:81], v[88:89], v[100:101]
	v_pk_fma_f32 v[78:79], v[78:79], v[86:87], v[98:99]
	s_waitcnt vmcnt(0)
	v_pk_fma_f32 v[76:77], v[76:77], v[84:85], v[104:105]
	v_pk_fma_f32 v[74:75], v[74:75], v[82:83], v[102:103]
	v_pk_mul_f32 v[100:101], v[140:141], v[80:81]
	v_pk_mul_f32 v[98:99], v[144:145], v[78:79]
	global_store_dwordx4 v[108:109], v[78:81], off
	global_store_dwordx4 v[108:109], v[74:77], off offset:16
	v_pk_mul_f32 v[102:103], v[138:139], v[76:77]
	v_pk_mul_f32 v[104:105], v[142:143], v[74:75]
	v_cvt_pk_bf16_f32 v98, v98, v99
	v_cvt_pk_bf16_f32 v99, v100, v101
	v_mul_f32_e32 v79, v79, v79
	v_cvt_pk_bf16_f32 v100, v104, v105
	v_cvt_pk_bf16_f32 v101, v102, v103
	global_store_dwordx4 v[106:107], v[98:101], off
	global_load_dwordx4 v[98:101], v[110:111], off offset:512
	s_nop 0
	global_load_dwordx4 v[102:105], v[110:111], off offset:528
	v_mul_f32_e32 v81, v81, v81
	v_mul_f32_e32 v75, v75, v75
	v_fmac_f32_e32 v79, v78, v78
	v_fmac_f32_e32 v81, v80, v80
	v_mul_f32_e32 v77, v77, v77
	v_fmac_f32_e32 v75, v74, v74
	v_add_f32_e32 v74, v79, v81
	v_fmac_f32_e32 v77, v76, v76
	v_add_f32_e32 v74, v74, v75
	v_add_f32_e32 v74, v77, v74
	s_waitcnt vmcnt(1)
	v_pk_fma_f32 v[72:73], v[72:73], v[96:97], v[100:101]
	v_pk_fma_f32 v[70:71], v[70:71], v[94:95], v[98:99]
	s_waitcnt vmcnt(0)
	v_pk_fma_f32 v[66:67], v[66:67], v[90:91], v[102:103]
	v_mul_f32_e32 v75, v71, v71
	v_mul_f32_e32 v76, v73, v73
	v_pk_fma_f32 v[68:69], v[68:69], v[92:93], v[104:105]
	v_mul_f32_e32 v77, v67, v67
	v_fmac_f32_e32 v75, v70, v70
	v_fmac_f32_e32 v76, v72, v72
	v_mul_f32_e32 v78, v69, v69
	v_fmac_f32_e32 v77, v66, v66
	v_add_f32_e32 v75, v75, v76
	v_fmac_f32_e32 v78, v68, v68
	v_add_f32_e32 v75, v75, v77
	v_add_f32_e32 v75, v78, v75
	v_add_f32_e32 v78, v74, v75
	ds_bpermute_b32 v79, v201, v78
	global_store_dwordx4 v[108:109], v[70:73], off offset:512
	global_store_dwordx4 v[108:109], v[66:69], off offset:528
	v_pk_mul_f32 v[76:77], v[160:161], v[66:67]
	v_pk_mul_f32 v[70:71], v[178:179], v[70:71]
	v_pk_mul_f32 v[72:73], v[180:181], v[72:73]
	s_waitcnt lgkmcnt(0)
	v_add_f32_e32 v66, v78, v79
	ds_bpermute_b32 v67, v132, v66
	v_pk_mul_f32 v[74:75], v[158:159], v[68:69]
	v_cvt_pk_bf16_f32 v68, v70, v71
	v_cvt_pk_bf16_f32 v69, v72, v73
	v_cvt_pk_bf16_f32 v70, v76, v77
	s_nop 0
	v_cvt_pk_bf16_f32 v71, v74, v75
	global_store_dwordx4 v[106:107], v[68:71], off offset:256
	s_and_saveexec_b64 s[26:27], s[4:5]
	s_cbranch_execz .LBB0_662
	s_waitcnt lgkmcnt(0)
	v_add_f32_e32 v66, v66, v67
	v_mov_b32_e32 v246, v66
.LBB0_662:
	s_or_b64 exec, exec, s[26:27]
	s_mov_b64 s[26:27], 0x20000
	v_lshl_add_u64 v[74:75], v[156:157], 0, s[26:27]
	v_lshlrev_b64 v[76:77], 2, v[74:75]
	v_lshl_add_u64 v[78:79], s[14:15], 0, v[76:77]
	s_waitcnt lgkmcnt(0)
	global_load_dwordx4 v[66:69], v[78:79], off
	global_load_dwordx4 v[70:73], v[78:79], off offset:16
	v_lshl_add_u64 v[74:75], v[74:75], 1, s[10:11]
	v_lshl_add_u64 v[76:77], s[8:9], 0, v[76:77]
	s_waitcnt vmcnt(1)
	v_pk_fma_f32 v[64:65], v[64:65], v[88:89], v[68:69]
	v_pk_fma_f32 v[62:63], v[62:63], v[86:87], v[66:67]
	s_waitcnt vmcnt(0)
	v_pk_fma_f32 v[60:61], v[60:61], v[84:85], v[72:73]
	v_pk_fma_f32 v[58:59], v[58:59], v[82:83], v[70:71]
	v_pk_mul_f32 v[68:69], v[140:141], v[64:65]
	v_pk_mul_f32 v[66:67], v[144:145], v[62:63]
	global_store_dwordx4 v[76:77], v[62:65], off
	global_store_dwordx4 v[76:77], v[58:61], off offset:16
	v_pk_mul_f32 v[70:71], v[138:139], v[60:61]
	v_pk_mul_f32 v[72:73], v[142:143], v[58:59]
	v_cvt_pk_bf16_f32 v66, v66, v67
	v_cvt_pk_bf16_f32 v67, v68, v69
	v_mul_f32_e32 v63, v63, v63
	v_cvt_pk_bf16_f32 v68, v72, v73
	v_cvt_pk_bf16_f32 v69, v70, v71
	global_store_dwordx4 v[74:75], v[66:69], off
	global_load_dwordx4 v[66:69], v[78:79], off offset:512
	s_nop 0
	global_load_dwordx4 v[70:73], v[78:79], off offset:528
	v_mul_f32_e32 v65, v65, v65
	v_mul_f32_e32 v59, v59, v59
	v_fmac_f32_e32 v63, v62, v62
	v_fmac_f32_e32 v65, v64, v64
	v_mul_f32_e32 v61, v61, v61
	v_fmac_f32_e32 v59, v58, v58
	v_add_f32_e32 v58, v63, v65
	v_fmac_f32_e32 v61, v60, v60
	v_add_f32_e32 v58, v58, v59
	v_add_f32_e32 v58, v61, v58
	s_waitcnt vmcnt(1)
	v_pk_fma_f32 v[56:57], v[56:57], v[96:97], v[68:69]
	v_pk_fma_f32 v[54:55], v[54:55], v[94:95], v[66:67]
	s_waitcnt vmcnt(0)
	v_pk_fma_f32 v[50:51], v[50:51], v[90:91], v[70:71]
	v_mul_f32_e32 v59, v55, v55
	v_mul_f32_e32 v60, v57, v57
	v_pk_fma_f32 v[52:53], v[52:53], v[92:93], v[72:73]
	v_mul_f32_e32 v61, v51, v51
	v_fmac_f32_e32 v59, v54, v54
	v_fmac_f32_e32 v60, v56, v56
	v_mul_f32_e32 v62, v53, v53
	v_fmac_f32_e32 v61, v50, v50
	v_add_f32_e32 v59, v59, v60
	v_fmac_f32_e32 v62, v52, v52
	v_add_f32_e32 v59, v59, v61
	v_add_f32_e32 v59, v62, v59
	v_add_f32_e32 v62, v58, v59
	ds_bpermute_b32 v63, v201, v62
	global_store_dwordx4 v[76:77], v[54:57], off offset:512
	global_store_dwordx4 v[76:77], v[50:53], off offset:528
	v_pk_mul_f32 v[60:61], v[160:161], v[50:51]
	v_pk_mul_f32 v[54:55], v[178:179], v[54:55]
	v_pk_mul_f32 v[56:57], v[180:181], v[56:57]
	s_waitcnt lgkmcnt(0)
	v_add_f32_e32 v50, v62, v63
	ds_bpermute_b32 v51, v132, v50
	v_pk_mul_f32 v[58:59], v[158:159], v[52:53]
	v_cvt_pk_bf16_f32 v52, v54, v55
	v_cvt_pk_bf16_f32 v53, v56, v57
	v_cvt_pk_bf16_f32 v54, v60, v61
	s_nop 0
	v_cvt_pk_bf16_f32 v55, v58, v59
	global_store_dwordx4 v[74:75], v[52:55], off offset:256
	s_and_saveexec_b64 s[26:27], s[4:5]
	s_cbranch_execz .LBB0_664
	s_waitcnt lgkmcnt(0)
	v_add_f32_e32 v50, v50, v51
	v_mov_b32_e32 v247, v50
; DI unsigned pk2(float lo, float hi) { return pg8::cvt_pk_bf16(lo, hi); }
;     DI void operator()(const f32x4 (&acc)[2][2][4][2], const Unit& u, int wr, int wc, int fr, int fq) const {
;     ...
;             for (int m = 0; m < 4; ++m) { const size_t r = (size_t)(row0 + ai * 128 + m * 16); float ss = 0.f;
; #pragma unroll
;                 for (int bj = 0; bj < 2; ++bj) { const size_t off = r * 1024 + col0 + bj * 128;
;                     f32x4 v0 = *(const f32x4*)(base + off), v1 = *(const f32x4*)(base + off + 4);
;                     v0 += g[bj][0] * acc[ai][bj][m][0]; v1 += g[bj][1] * acc[ai][bj][m][1];
;                     *(f32x4*)(out + off) = v0; *(f32x4*)(out + off + 4) = v1;
;                     ss += (v0[0] * v0[0] + v0[1] * v0[1]) + (v0[2] * v0[2] + v0[3] * v0[3]) + (v1[0] * v1[0] + v1[1] * v1[1]) + (v1[2] * v1[2] + v1[3] * v1[3]);
;                     const f32x4 u0 = v0 * gm[bj][0], u1 = v1 * gm[bj][1];
;                     v4u w; w.x = pk2(u0[0], u0[1]); w.y = pk2(u0[2], u0[3]); w.z = pk2(u1[0], u1[1]); w.w = pk2(u1[2], u1[3]);
;                     *(v4u*)(U2 + off) = w; }
;                 ss += __shfl_xor(ss, 16); ss += __shfl_xor(ss, 32);
;                 if (fq == 0) atomicAdd(rowss + r, ss); }
.LBB0_664:
	s_or_b64 exec, exec, s[26:27]
	s_mov_b64 s[26:27], 0x24000
	v_lshl_add_u64 v[58:59], v[156:157], 0, s[26:27]
	v_lshlrev_b64 v[60:61], 2, v[58:59]
	v_lshl_add_u64 v[62:63], s[14:15], 0, v[60:61]
	s_waitcnt lgkmcnt(0)
	global_load_dwordx4 v[50:53], v[62:63], off
	global_load_dwordx4 v[54:57], v[62:63], off offset:16
	v_lshl_add_u64 v[58:59], v[58:59], 1, s[10:11]
	v_lshl_add_u64 v[60:61], s[8:9], 0, v[60:61]
	s_waitcnt vmcnt(1)
	v_pk_fma_f32 v[48:49], v[48:49], v[88:89], v[52:53]
	v_pk_fma_f32 v[46:47], v[46:47], v[86:87], v[50:51]
	s_waitcnt vmcnt(0)
	v_pk_fma_f32 v[44:45], v[44:45], v[84:85], v[56:57]
	v_pk_fma_f32 v[42:43], v[42:43], v[82:83], v[54:55]
	v_pk_mul_f32 v[52:53], v[140:141], v[48:49]
	v_pk_mul_f32 v[50:51], v[144:145], v[46:47]
	global_store_dwordx4 v[60:61], v[46:49], off
	global_store_dwordx4 v[60:61], v[42:45], off offset:16
	v_pk_mul_f32 v[54:55], v[138:139], v[44:45]
	v_pk_mul_f32 v[56:57], v[142:143], v[42:43]
	v_cvt_pk_bf16_f32 v50, v50, v51
	v_cvt_pk_bf16_f32 v51, v52, v53
	v_mul_f32_e32 v47, v47, v47
	v_cvt_pk_bf16_f32 v52, v56, v57
	v_cvt_pk_bf16_f32 v53, v54, v55
	global_store_dwordx4 v[58:59], v[50:53], off
	global_load_dwordx4 v[50:53], v[62:63], off offset:512
	s_nop 0
	global_load_dwordx4 v[54:57], v[62:63], off offset:528
	v_mul_f32_e32 v49, v49, v49
	v_mul_f32_e32 v43, v43, v43
	v_fmac_f32_e32 v47, v46, v46
	v_fmac_f32_e32 v49, v48, v48
	v_mul_f32_e32 v45, v45, v45
	v_fmac_f32_e32 v43, v42, v42
	v_add_f32_e32 v42, v47, v49
	v_fmac_f32_e32 v45, v44, v44
	v_add_f32_e32 v42, v42, v43
	v_add_f32_e32 v42, v45, v42
	s_waitcnt vmcnt(1)
	v_pk_fma_f32 v[40:41], v[40:41], v[96:97], v[52:53]
	v_pk_fma_f32 v[38:39], v[38:39], v[94:95], v[50:51]
	s_waitcnt vmcnt(0)
	v_pk_fma_f32 v[34:35], v[34:35], v[90:91], v[54:55]
	v_mul_f32_e32 v43, v39, v39
	v_mul_f32_e32 v44, v41, v41
	v_pk_fma_f32 v[36:37], v[36:37], v[92:93], v[56:57]
	v_mul_f32_e32 v45, v35, v35
	v_fmac_f32_e32 v43, v38, v38
	v_fmac_f32_e32 v44, v40, v40
	v_mul_f32_e32 v46, v37, v37
	v_fmac_f32_e32 v45, v34, v34
	v_add_f32_e32 v43, v43, v44
	v_fmac_f32_e32 v46, v36, v36
	v_add_f32_e32 v43, v43, v45
	v_add_f32_e32 v43, v46, v43
	v_add_f32_e32 v46, v42, v43
	ds_bpermute_b32 v47, v201, v46
	global_store_dwordx4 v[60:61], v[38:41], off offset:512
	global_store_dwordx4 v[60:61], v[34:37], off offset:528
	v_pk_mul_f32 v[44:45], v[160:161], v[34:35]
	v_pk_mul_f32 v[38:39], v[178:179], v[38:39]
	v_pk_mul_f32 v[40:41], v[180:181], v[40:41]
	s_waitcnt lgkmcnt(0)
	v_add_f32_e32 v34, v46, v47
	ds_bpermute_b32 v35, v132, v34
	v_pk_mul_f32 v[42:43], v[158:159], v[36:37]
	v_cvt_pk_bf16_f32 v36, v38, v39
	v_cvt_pk_bf16_f32 v37, v40, v41
	v_cvt_pk_bf16_f32 v38, v44, v45
	s_nop 0
	v_cvt_pk_bf16_f32 v39, v42, v43
	global_store_dwordx4 v[58:59], v[36:39], off offset:256
	s_and_saveexec_b64 s[26:27], s[4:5]
	s_cbranch_execz .LBB0_666
	s_waitcnt lgkmcnt(0)
	v_add_f32_e32 v34, v34, v35
	v_mov_b32_e32 v206, v34
.LBB0_666:
	s_or_b64 exec, exec, s[26:27]
	s_mov_b64 s[26:27], 0x28000
	v_lshl_add_u64 v[42:43], v[156:157], 0, s[26:27]
	v_lshlrev_b64 v[44:45], 2, v[42:43]
	v_lshl_add_u64 v[46:47], s[14:15], 0, v[44:45]
	s_waitcnt lgkmcnt(0)
	global_load_dwordx4 v[34:37], v[46:47], off
	global_load_dwordx4 v[38:41], v[46:47], off offset:16
	v_lshl_add_u64 v[42:43], v[42:43], 1, s[10:11]
	v_lshl_add_u64 v[44:45], s[8:9], 0, v[44:45]
	s_waitcnt vmcnt(1)
	v_pk_fma_f32 v[32:33], v[32:33], v[88:89], v[36:37]
	v_pk_fma_f32 v[30:31], v[30:31], v[86:87], v[34:35]
	s_waitcnt vmcnt(0)
	v_pk_fma_f32 v[28:29], v[28:29], v[84:85], v[40:41]
	v_pk_fma_f32 v[26:27], v[26:27], v[82:83], v[38:39]
	v_pk_mul_f32 v[36:37], v[140:141], v[32:33]
	v_pk_mul_f32 v[34:35], v[144:145], v[30:31]
	global_store_dwordx4 v[44:45], v[30:33], off
	global_store_dwordx4 v[44:45], v[26:29], off offset:16
	v_pk_mul_f32 v[38:39], v[138:139], v[28:29]
	v_pk_mul_f32 v[40:41], v[142:143], v[26:27]
	v_cvt_pk_bf16_f32 v34, v34, v35
	v_cvt_pk_bf16_f32 v35, v36, v37
	v_mul_f32_e32 v31, v31, v31
	v_cvt_pk_bf16_f32 v36, v40, v41
	v_cvt_pk_bf16_f32 v37, v38, v39
	global_store_dwordx4 v[42:43], v[34:37], off
	global_load_dwordx4 v[34:37], v[46:47], off offset:512
	s_nop 0
	global_load_dwordx4 v[38:41], v[46:47], off offset:528
	v_mul_f32_e32 v33, v33, v33
	v_mul_f32_e32 v27, v27, v27
	v_fmac_f32_e32 v31, v30, v30
	v_fmac_f32_e32 v33, v32, v32
	v_mul_f32_e32 v29, v29, v29
	v_fmac_f32_e32 v27, v26, v26
	v_add_f32_e32 v26, v31, v33
	v_fmac_f32_e32 v29, v28, v28
	v_add_f32_e32 v26, v26, v27
	v_add_f32_e32 v26, v29, v26
	s_waitcnt vmcnt(1)
	v_pk_fma_f32 v[24:25], v[24:25], v[96:97], v[36:37]
	v_pk_fma_f32 v[22:23], v[22:23], v[94:95], v[34:35]
	s_waitcnt vmcnt(0)
	v_pk_fma_f32 v[18:19], v[18:19], v[90:91], v[38:39]
	v_mul_f32_e32 v27, v23, v23
	v_mul_f32_e32 v28, v25, v25
	v_pk_fma_f32 v[20:21], v[20:21], v[92:93], v[40:41]
	v_mul_f32_e32 v29, v19, v19
	v_fmac_f32_e32 v27, v22, v22
	v_fmac_f32_e32 v28, v24, v24
	v_mul_f32_e32 v30, v21, v21
	v_fmac_f32_e32 v29, v18, v18
	v_add_f32_e32 v27, v27, v28
	v_fmac_f32_e32 v30, v20, v20
	v_add_f32_e32 v27, v27, v29
	v_add_f32_e32 v27, v30, v27
	v_add_f32_e32 v30, v26, v27
	ds_bpermute_b32 v31, v201, v30
	global_store_dwordx4 v[44:45], v[22:25], off offset:512
	global_store_dwordx4 v[44:45], v[18:21], off offset:528
	v_pk_mul_f32 v[28:29], v[160:161], v[18:19]
	v_pk_mul_f32 v[22:23], v[178:179], v[22:23]
	v_pk_mul_f32 v[24:25], v[180:181], v[24:25]
	s_waitcnt lgkmcnt(0)
	v_add_f32_e32 v18, v30, v31
	ds_bpermute_b32 v19, v132, v18
	v_pk_mul_f32 v[26:27], v[158:159], v[20:21]
	v_cvt_pk_bf16_f32 v20, v22, v23
	v_cvt_pk_bf16_f32 v21, v24, v25
	v_cvt_pk_bf16_f32 v22, v28, v29
	s_nop 0
	v_cvt_pk_bf16_f32 v23, v26, v27
	global_store_dwordx4 v[42:43], v[20:23], off offset:256
	s_and_saveexec_b64 s[26:27], s[4:5]
	s_cbranch_execz .LBB0_668
	s_waitcnt lgkmcnt(0)
	v_add_f32_e32 v18, v18, v19
	v_mov_b32_e32 v207, v18
; DI unsigned pk2(float lo, float hi) { return pg8::cvt_pk_bf16(lo, hi); }
;     DI void operator()(const f32x4 (&acc)[2][2][4][2], const Unit& u, int wr, int wc, int fr, int fq) const {
;     ...
;             for (int m = 0; m < 4; ++m) { const size_t r = (size_t)(row0 + ai * 128 + m * 16); float ss = 0.f;
; #pragma unroll
;                 for (int bj = 0; bj < 2; ++bj) { const size_t off = r * 1024 + col0 + bj * 128;
;                     f32x4 v0 = *(const f32x4*)(base + off), v1 = *(const f32x4*)(base + off + 4);
;                     v0 += g[bj][0] * acc[ai][bj][m][0]; v1 += g[bj][1] * acc[ai][bj][m][1];
;                     *(f32x4*)(out + off) = v0; *(f32x4*)(out + off + 4) = v1;
;                     ss += (v0[0] * v0[0] + v0[1] * v0[1]) + (v0[2] * v0[2] + v0[3] * v0[3]) + (v1[0] * v1[0] + v1[1] * v1[1]) + (v1[2] * v1[2] + v1[3] * v1[3]);
;                     const f32x4 u0 = v0 * gm[bj][0], u1 = v1 * gm[bj][1];
;                     v4u w; w.x = pk2(u0[0], u0[1]); w.y = pk2(u0[2], u0[3]); w.z = pk2(u1[0], u1[1]); w.w = pk2(u1[2], u1[3]);
;                     *(v4u*)(U2 + off) = w; }
;                 ss += __shfl_xor(ss, 16); ss += __shfl_xor(ss, 32);
;                 if (fq == 0) atomicAdd(rowss + r, ss); }
.LBB0_668:
	s_or_b64 exec, exec, s[26:27]
	s_mov_b64 s[26:27], 0x2c000
	v_lshl_add_u64 v[26:27], v[156:157], 0, s[26:27]
	v_lshlrev_b64 v[28:29], 2, v[26:27]
	v_lshl_add_u64 v[30:31], s[14:15], 0, v[28:29]
	s_waitcnt lgkmcnt(0)
	global_load_dwordx4 v[18:21], v[30:31], off
	global_load_dwordx4 v[22:25], v[30:31], off offset:16
	v_lshl_add_u64 v[26:27], v[26:27], 1, s[10:11]
	v_lshl_add_u64 v[28:29], s[8:9], 0, v[28:29]
	s_waitcnt vmcnt(1)
	v_pk_fma_f32 v[16:17], v[16:17], v[88:89], v[20:21]
	v_pk_fma_f32 v[14:15], v[14:15], v[86:87], v[18:19]
	s_waitcnt vmcnt(0)
	v_pk_fma_f32 v[12:13], v[12:13], v[84:85], v[24:25]
	v_pk_fma_f32 v[10:11], v[10:11], v[82:83], v[22:23]
	v_pk_mul_f32 v[20:21], v[140:141], v[16:17]
	v_pk_mul_f32 v[18:19], v[144:145], v[14:15]
	global_store_dwordx4 v[28:29], v[14:17], off
	global_store_dwordx4 v[28:29], v[10:13], off offset:16
	v_pk_mul_f32 v[22:23], v[138:139], v[12:13]
	v_pk_mul_f32 v[24:25], v[142:143], v[10:11]
	v_cvt_pk_bf16_f32 v18, v18, v19
	v_cvt_pk_bf16_f32 v19, v20, v21
	v_mul_f32_e32 v15, v15, v15
	v_cvt_pk_bf16_f32 v20, v24, v25
	v_cvt_pk_bf16_f32 v21, v22, v23
	global_store_dwordx4 v[26:27], v[18:21], off
	global_load_dwordx4 v[18:21], v[30:31], off offset:512
	s_nop 0
	global_load_dwordx4 v[22:25], v[30:31], off offset:528
	v_mul_f32_e32 v17, v17, v17
	v_mul_f32_e32 v11, v11, v11
	v_fmac_f32_e32 v15, v14, v14
	v_fmac_f32_e32 v17, v16, v16
	v_mul_f32_e32 v13, v13, v13
	v_fmac_f32_e32 v11, v10, v10
	v_add_f32_e32 v10, v15, v17
	v_fmac_f32_e32 v13, v12, v12
	v_add_f32_e32 v10, v10, v11
	v_add_f32_e32 v10, v13, v10
	s_waitcnt vmcnt(1)
	v_pk_fma_f32 v[8:9], v[8:9], v[96:97], v[20:21]
	v_pk_fma_f32 v[6:7], v[6:7], v[94:95], v[18:19]
	s_waitcnt vmcnt(0)
	v_pk_fma_f32 v[2:3], v[2:3], v[90:91], v[22:23]
	v_mul_f32_e32 v11, v7, v7
	v_mul_f32_e32 v12, v9, v9
	v_pk_fma_f32 v[4:5], v[4:5], v[92:93], v[24:25]
	v_mul_f32_e32 v13, v3, v3
	v_fmac_f32_e32 v11, v6, v6
	v_fmac_f32_e32 v12, v8, v8
	v_mul_f32_e32 v14, v5, v5
	v_fmac_f32_e32 v13, v2, v2
	v_add_f32_e32 v11, v11, v12
	v_fmac_f32_e32 v14, v4, v4
	v_add_f32_e32 v11, v11, v13
	v_add_f32_e32 v11, v14, v11
	v_add_f32_e32 v14, v10, v11
	ds_bpermute_b32 v15, v201, v14
	global_store_dwordx4 v[28:29], v[6:9], off offset:512
	global_store_dwordx4 v[28:29], v[2:5], off offset:528
	v_pk_mul_f32 v[12:13], v[160:161], v[2:3]
	v_pk_mul_f32 v[6:7], v[178:179], v[6:7]
	v_pk_mul_f32 v[8:9], v[180:181], v[8:9]
	s_waitcnt lgkmcnt(0)
	v_add_f32_e32 v2, v14, v15
	ds_bpermute_b32 v3, v132, v2
	v_pk_mul_f32 v[10:11], v[158:159], v[4:5]
	v_cvt_pk_bf16_f32 v4, v6, v7
	v_cvt_pk_bf16_f32 v5, v8, v9
	v_cvt_pk_bf16_f32 v6, v12, v13
	s_nop 0
	v_cvt_pk_bf16_f32 v7, v10, v11
	global_store_dwordx4 v[26:27], v[4:7], off offset:256
	s_and_saveexec_b64 s[26:27], s[4:5]
	s_cbranch_execz .LBB0_670
	s_waitcnt lgkmcnt(0)
	v_add_f32_e32 v2, v2, v3
	global_atomic_add_f32 v[130:131], v2, off offset:704
	global_atomic_add_f32 v[130:131], v248, off
	global_atomic_add_f32 v[130:131], v244, off offset:64
	global_atomic_add_f32 v[130:131], v245, off offset:128
	global_atomic_add_f32 v[130:131], v246, off offset:192
	global_atomic_add_f32 v[130:131], v247, off offset:512
	global_atomic_add_f32 v[130:131], v206, off offset:576
	global_atomic_add_f32 v[130:131], v207, off offset:640
